# passC walk + flat->global + SB finalize: 8 gate loads behind one wait
# speedup vs baseline: 1.0021x; 1.0021x over previous
; DI unsigned pk2(float lo, float hi) { f32x2_t f = {lo, hi}; bf16x2_t v = __builtin_convertvector(f, bf16x2_t); return __builtin_bit_cast(unsigned, v); }
; DI float silu(float v) { return v / (1.f + __expf(-v)); }
; DI void sb_phase(const Params& P, LAS unsigned char* lds) {
;     ...
;             { const bf16_t* gp = Uall + ((size_t)b * SEQ + tq) * LDU_O + 6144 + h * 128 + 4 * g; bf16_t* yp = (bf16_t*)Uall + ((size_t)b * SEQ + tq) * LDU_O + h * 128 + 4 * g;
; #pragma unroll
;               for (int vt = 0; vt < 8; ++vt) { const u32x2 gv = *(const u32x2*)(gp + 16 * vt);
;                   u32x2 wv; wv.x = pk2(o[vt][0] * silu(bflo(gv.x)), o[vt][1] * silu(bfhi(gv.x))); wv.y = pk2(o[vt][2] * silu(bflo(gv.y)), o[vt][3] * silu(bfhi(gv.y)));
;                   *(u32x2*)(yp + 16 * vt) = wv; } }
.LBB0_77:
	s_ashr_i32 s35, s34, 31
	s_lshl_b64 s[6:7], s[34:35], 27
	v_ashrrev_i32_e32 v185, 31, v184
	s_add_u32 s6, s20, s6
	s_addc_u32 s7, s21, s7
	v_lshlrev_b64 v[98:99], 14, v[184:185]
	v_lshl_add_u64 v[98:99], s[6:7], 0, v[98:99]
	s_lshl_b32 s10, s8, 1
	v_lshlrev_b32_e32 v0, 1, v178
	v_lshl_add_u64 v[98:99], v[98:99], 0, s[10:11]
	v_lshl_add_u64 v[98:99], v[98:99], 0, v[0:1]
	v_add_co_u32_e32 v102, vcc, s86, v98
	s_mov_b64 s[6:7], 0x3000
	s_nop 0
	v_addc_co_u32_e32 v103, vcc, 0, v99, vcc
	global_load_dwordx2 v[214:215], v[102:103], off
	global_load_dwordx2 v[216:217], v[102:103], off offset:32
	global_load_dwordx2 v[218:219], v[102:103], off offset:64
	global_load_dwordx2 v[220:221], v[102:103], off offset:96
	global_load_dwordx2 v[222:223], v[102:103], off offset:128
	global_load_dwordx2 v[224:225], v[102:103], off offset:160
	global_load_dwordx2 v[226:227], v[102:103], off offset:192
	global_load_dwordx2 v[232:233], v[102:103], off offset:224
	v_lshl_add_u64 v[100:101], v[98:99], 0, s[6:7]
	s_cmpk_lt_i32 s17, 0x800
	s_mov_b32 s35, 0
	s_mov_b32 s58, s17
	s_waitcnt vmcnt(0) lgkmcnt(0)
	v_mov_b32_e32 v102, v214
	v_mov_b32_e32 v103, v215
	v_lshlrev_b32_e32 v0, 16, v102
	v_and_b32_e32 v102, 0xffff0000, v102
	v_mul_f32_e32 v104, 0xbfb8aa3b, v0
	v_mul_f32_e32 v105, 0xbfb8aa3b, v102
	v_exp_f32_e32 v104, v104
	v_exp_f32_e32 v105, v105
	s_nop 0
	v_pk_add_f32 v[104:105], v[104:105], 1.0 op_sel_hi:[1,0]
	s_nop 0
	v_div_scale_f32 v106, s[6:7], v105, v105, v102
	v_rcp_f32_e32 v107, v106
	s_nop 0
	v_fma_f32 v108, -v106, v107, 1.0
	v_fmac_f32_e32 v107, v108, v107
	v_div_scale_f32 v108, vcc, v102, v105, v102
	v_mul_f32_e32 v109, v108, v107
	v_fma_f32 v110, -v106, v109, v108
	v_fmac_f32_e32 v109, v110, v107
	v_fma_f32 v106, -v106, v109, v108
	v_div_fmas_f32 v106, v106, v107, v109
	v_div_fixup_f32 v105, v106, v105, v102
	v_div_scale_f32 v102, s[6:7], v104, v104, v0
	v_rcp_f32_e32 v106, v102
	v_mov_b64_e32 v[112:113], v[16:17]
	v_mov_b64_e32 v[110:111], v[14:15]
	v_fma_f32 v107, -v102, v106, 1.0
	v_fmac_f32_e32 v106, v107, v106
	v_div_scale_f32 v107, vcc, v0, v104, v0
	v_mul_f32_e32 v108, v107, v106
	v_fma_f32 v109, -v102, v108, v107
	v_fmac_f32_e32 v108, v109, v106
	v_fma_f32 v102, -v102, v108, v107
	v_div_fmas_f32 v102, v102, v106, v108
	v_div_fixup_f32 v104, v102, v104, v0
	v_pk_mul_f32 v[94:95], v[94:95], v[104:105]
	v_lshlrev_b32_e32 v0, 16, v103
	v_cvt_pk_bf16_f32 v94, v94, v95
	v_and_b32_e32 v95, 0xffff0000, v103
	v_mul_f32_e32 v102, 0xbfb8aa3b, v0
	v_mul_f32_e32 v103, 0xbfb8aa3b, v95
	v_exp_f32_e32 v102, v102
	v_exp_f32_e32 v103, v103
	s_nop 0
	v_pk_add_f32 v[102:103], v[102:103], 1.0 op_sel_hi:[1,0]
	s_nop 0
	v_div_scale_f32 v104, s[6:7], v103, v103, v95
	v_rcp_f32_e32 v105, v104
	s_nop 0
	v_fma_f32 v106, -v104, v105, 1.0
	v_fmac_f32_e32 v105, v106, v105
	v_div_scale_f32 v106, vcc, v95, v103, v95
	v_mul_f32_e32 v107, v106, v105
	v_fma_f32 v108, -v104, v107, v106
	v_fmac_f32_e32 v107, v108, v105
	v_fma_f32 v104, -v104, v107, v106
	v_div_fmas_f32 v104, v104, v105, v107
	v_div_fixup_f32 v103, v104, v103, v95
	v_div_scale_f32 v95, s[6:7], v102, v102, v0
	v_rcp_f32_e32 v104, v95
	s_nop 0
	v_fma_f32 v105, -v95, v104, 1.0
	v_fmac_f32_e32 v104, v105, v104
	v_div_scale_f32 v105, vcc, v0, v102, v0
	v_mul_f32_e32 v106, v105, v104
	v_fma_f32 v107, -v95, v106, v105
	v_fmac_f32_e32 v106, v107, v104
	v_fma_f32 v95, -v95, v106, v105
	v_div_fmas_f32 v95, v95, v104, v106
	v_div_fixup_f32 v102, v95, v102, v0
	v_pk_mul_f32 v[96:97], v[96:97], v[102:103]
	s_nop 0
	v_cvt_pk_bf16_f32 v95, v96, v97
	global_store_dwordx2 v[98:99], v[94:95], off
	v_mov_b32_e32 v94, v216
	v_mov_b32_e32 v95, v217
	v_lshlrev_b32_e32 v0, 16, v94
	v_and_b32_e32 v94, 0xffff0000, v94
	v_mul_f32_e32 v96, 0xbfb8aa3b, v0
	v_mul_f32_e32 v97, 0xbfb8aa3b, v94
	v_exp_f32_e32 v96, v96
	v_exp_f32_e32 v97, v97
	s_nop 0
	v_pk_add_f32 v[96:97], v[96:97], 1.0 op_sel_hi:[1,0]
	s_nop 0
	v_div_scale_f32 v102, s[6:7], v97, v97, v94
	v_rcp_f32_e32 v103, v102
	s_nop 0
	v_fma_f32 v104, -v102, v103, 1.0
	v_fmac_f32_e32 v103, v104, v103
	v_div_scale_f32 v104, vcc, v94, v97, v94
	v_mul_f32_e32 v105, v104, v103
	v_fma_f32 v106, -v102, v105, v104
	v_fmac_f32_e32 v105, v106, v103
	v_fma_f32 v102, -v102, v105, v104
	v_div_fmas_f32 v102, v102, v103, v105
	v_div_fixup_f32 v97, v102, v97, v94
	v_div_scale_f32 v94, s[6:7], v96, v96, v0
	v_rcp_f32_e32 v102, v94
	v_mov_b64_e32 v[108:109], v[12:13]
	v_mov_b64_e32 v[106:107], v[10:11]
	v_fma_f32 v103, -v94, v102, 1.0
	v_fmac_f32_e32 v102, v103, v102
	v_div_scale_f32 v103, vcc, v0, v96, v0
	v_mul_f32_e32 v104, v103, v102
	v_fma_f32 v105, -v94, v104, v103
	v_fmac_f32_e32 v104, v105, v102
	v_fma_f32 v94, -v94, v104, v103
	v_div_fmas_f32 v94, v94, v102, v104
	v_div_fixup_f32 v96, v94, v96, v0
	v_pk_mul_f32 v[90:91], v[90:91], v[96:97]
	v_lshlrev_b32_e32 v0, 16, v95
	v_cvt_pk_bf16_f32 v90, v90, v91
	v_and_b32_e32 v91, 0xffff0000, v95
	v_mul_f32_e32 v94, 0xbfb8aa3b, v0
	v_mul_f32_e32 v95, 0xbfb8aa3b, v91
	v_exp_f32_e32 v94, v94
	v_exp_f32_e32 v95, v95
	s_nop 0
	v_pk_add_f32 v[94:95], v[94:95], 1.0 op_sel_hi:[1,0]
	s_nop 0
	v_div_scale_f32 v96, s[6:7], v95, v95, v91
	v_rcp_f32_e32 v97, v96
	s_nop 0
	v_fma_f32 v102, -v96, v97, 1.0
	v_fmac_f32_e32 v97, v102, v97
	v_div_scale_f32 v102, vcc, v91, v95, v91
	v_mul_f32_e32 v103, v102, v97
	v_fma_f32 v104, -v96, v103, v102
	v_fmac_f32_e32 v103, v104, v97
	v_fma_f32 v96, -v96, v103, v102
	v_div_fmas_f32 v96, v96, v97, v103
	v_div_fixup_f32 v95, v96, v95, v91
	v_div_scale_f32 v91, s[6:7], v94, v94, v0
	v_rcp_f32_e32 v96, v91
	s_nop 0
	v_fma_f32 v97, -v91, v96, 1.0
	v_fmac_f32_e32 v96, v97, v96
	v_div_scale_f32 v97, vcc, v0, v94, v0
; DI unsigned pk2(float lo, float hi) { f32x2_t f = {lo, hi}; bf16x2_t v = __builtin_convertvector(f, bf16x2_t); return __builtin_bit_cast(unsigned, v); }
; DI float silu(float v) { return v / (1.f + __expf(-v)); }
; DI void sb_phase(const Params& P, LAS unsigned char* lds) {
;     ...
;               for (int vt = 0; vt < 8; ++vt) { const u32x2 gv = *(const u32x2*)(gp + 16 * vt);
;                   u32x2 wv; wv.x = pk2(o[vt][0] * silu(bflo(gv.x)), o[vt][1] * silu(bfhi(gv.x))); wv.y = pk2(o[vt][2] * silu(bflo(gv.y)), o[vt][3] * silu(bfhi(gv.y)));
;                   *(u32x2*)(yp + 16 * vt) = wv; } }
	v_mul_f32_e32 v102, v97, v96
	v_fma_f32 v103, -v91, v102, v97
	v_fmac_f32_e32 v102, v103, v96
	v_fma_f32 v91, -v91, v102, v97
	v_div_fmas_f32 v91, v91, v96, v102
	v_div_fixup_f32 v94, v91, v94, v0
	v_pk_mul_f32 v[92:93], v[92:93], v[94:95]
	s_nop 0
	v_cvt_pk_bf16_f32 v91, v92, v93
	global_store_dwordx2 v[98:99], v[90:91], off offset:32
	v_mov_b32_e32 v90, v218
	v_mov_b32_e32 v91, v219
	v_lshlrev_b32_e32 v0, 16, v90
	v_and_b32_e32 v90, 0xffff0000, v90
	v_mul_f32_e32 v92, 0xbfb8aa3b, v0
	v_mul_f32_e32 v93, 0xbfb8aa3b, v90
	v_exp_f32_e32 v92, v92
	v_exp_f32_e32 v93, v93
	s_nop 0
	v_pk_add_f32 v[92:93], v[92:93], 1.0 op_sel_hi:[1,0]
	s_nop 0
	v_div_scale_f32 v94, s[6:7], v93, v93, v90
	v_rcp_f32_e32 v95, v94
	s_nop 0
	v_fma_f32 v96, -v94, v95, 1.0
	v_fmac_f32_e32 v95, v96, v95
	v_div_scale_f32 v96, vcc, v90, v93, v90
	v_mul_f32_e32 v97, v96, v95
	v_fma_f32 v102, -v94, v97, v96
	v_fmac_f32_e32 v97, v102, v95
	v_fma_f32 v94, -v94, v97, v96
	v_div_fmas_f32 v94, v94, v95, v97
	v_div_fixup_f32 v93, v94, v93, v90
	v_div_scale_f32 v90, s[6:7], v92, v92, v0
	v_rcp_f32_e32 v94, v90
	v_mov_b64_e32 v[104:105], v[8:9]
	v_mov_b64_e32 v[102:103], v[6:7]
	v_fma_f32 v95, -v90, v94, 1.0
	v_fmac_f32_e32 v94, v95, v94
	v_div_scale_f32 v95, vcc, v0, v92, v0
	v_mul_f32_e32 v96, v95, v94
	v_fma_f32 v97, -v90, v96, v95
	v_fmac_f32_e32 v96, v97, v94
	v_fma_f32 v90, -v90, v96, v95
	v_div_fmas_f32 v90, v90, v94, v96
	v_div_fixup_f32 v92, v90, v92, v0
	v_pk_mul_f32 v[86:87], v[86:87], v[92:93]
	v_lshlrev_b32_e32 v0, 16, v91
	v_cvt_pk_bf16_f32 v86, v86, v87
	v_and_b32_e32 v87, 0xffff0000, v91
	v_mul_f32_e32 v90, 0xbfb8aa3b, v0
	v_mul_f32_e32 v91, 0xbfb8aa3b, v87
	v_exp_f32_e32 v90, v90
	v_exp_f32_e32 v91, v91
	s_nop 0
	v_pk_add_f32 v[90:91], v[90:91], 1.0 op_sel_hi:[1,0]
	s_nop 0
	v_div_scale_f32 v92, s[6:7], v91, v91, v87
	v_rcp_f32_e32 v93, v92
	s_nop 0
	v_fma_f32 v94, -v92, v93, 1.0
	v_fmac_f32_e32 v93, v94, v93
	v_div_scale_f32 v94, vcc, v87, v91, v87
	v_mul_f32_e32 v95, v94, v93
	v_fma_f32 v96, -v92, v95, v94
	v_fmac_f32_e32 v95, v96, v93
	v_fma_f32 v92, -v92, v95, v94
	v_div_fmas_f32 v92, v92, v93, v95
	v_div_fixup_f32 v91, v92, v91, v87
	v_div_scale_f32 v87, s[6:7], v90, v90, v0
	v_rcp_f32_e32 v92, v87
	s_nop 0
	v_fma_f32 v93, -v87, v92, 1.0
	v_fmac_f32_e32 v92, v93, v92
	v_div_scale_f32 v93, vcc, v0, v90, v0
	v_mul_f32_e32 v94, v93, v92
	v_fma_f32 v95, -v87, v94, v93
	v_fmac_f32_e32 v94, v95, v92
	v_fma_f32 v87, -v87, v94, v93
	v_div_fmas_f32 v87, v87, v92, v94
	v_div_fixup_f32 v90, v87, v90, v0
	v_pk_mul_f32 v[88:89], v[88:89], v[90:91]
	s_nop 0
	v_cvt_pk_bf16_f32 v87, v88, v89
	global_store_dwordx2 v[98:99], v[86:87], off offset:64
	v_mov_b32_e32 v86, v220
	v_mov_b32_e32 v87, v221
	v_lshlrev_b32_e32 v0, 16, v86
	v_and_b32_e32 v86, 0xffff0000, v86
	v_mul_f32_e32 v88, 0xbfb8aa3b, v0
	v_mul_f32_e32 v89, 0xbfb8aa3b, v86
	v_exp_f32_e32 v88, v88
	v_exp_f32_e32 v89, v89
	s_nop 0
	v_pk_add_f32 v[88:89], v[88:89], 1.0 op_sel_hi:[1,0]
	s_nop 0
	v_div_scale_f32 v90, s[6:7], v89, v89, v86
	v_rcp_f32_e32 v91, v90
	s_nop 0
	v_fma_f32 v92, -v90, v91, 1.0
	v_fmac_f32_e32 v91, v92, v91
	v_div_scale_f32 v92, vcc, v86, v89, v86
	v_mul_f32_e32 v93, v92, v91
	v_fma_f32 v94, -v90, v93, v92
	v_fmac_f32_e32 v93, v94, v91
	v_fma_f32 v90, -v90, v93, v92
	v_div_fmas_f32 v90, v90, v91, v93
	v_div_fixup_f32 v89, v90, v89, v86
	v_div_scale_f32 v86, s[6:7], v88, v88, v0
	v_rcp_f32_e32 v90, v86
	s_nop 0
	v_fma_f32 v91, -v86, v90, 1.0
	v_fmac_f32_e32 v90, v91, v90
	v_div_scale_f32 v91, vcc, v0, v88, v0
	v_mul_f32_e32 v92, v91, v90
	v_fma_f32 v93, -v86, v92, v91
	v_fmac_f32_e32 v92, v93, v90
	v_fma_f32 v86, -v86, v92, v91
	v_div_fmas_f32 v86, v86, v90, v92
	v_div_fixup_f32 v88, v86, v88, v0
	v_pk_mul_f32 v[82:83], v[82:83], v[88:89]
	v_lshlrev_b32_e32 v0, 16, v87
	v_cvt_pk_bf16_f32 v82, v82, v83
	v_and_b32_e32 v83, 0xffff0000, v87
	v_mul_f32_e32 v86, 0xbfb8aa3b, v0
	v_mul_f32_e32 v87, 0xbfb8aa3b, v83
	v_exp_f32_e32 v86, v86
	v_exp_f32_e32 v87, v87
	s_nop 0
	v_pk_add_f32 v[86:87], v[86:87], 1.0 op_sel_hi:[1,0]
	s_nop 0
	v_div_scale_f32 v88, s[6:7], v87, v87, v83
	v_rcp_f32_e32 v89, v88
	s_nop 0
	v_fma_f32 v90, -v88, v89, 1.0
	v_fmac_f32_e32 v89, v90, v89
	v_div_scale_f32 v90, vcc, v83, v87, v83
	v_mul_f32_e32 v91, v90, v89
	v_fma_f32 v92, -v88, v91, v90
	v_fmac_f32_e32 v91, v92, v89
	v_fma_f32 v88, -v88, v91, v90
	v_div_fmas_f32 v88, v88, v89, v91
	v_div_fixup_f32 v87, v88, v87, v83
	v_div_scale_f32 v83, s[6:7], v86, v86, v0
	v_rcp_f32_e32 v88, v83
	s_nop 0
	v_fma_f32 v89, -v83, v88, 1.0
	v_fmac_f32_e32 v88, v89, v88
	v_div_scale_f32 v89, vcc, v0, v86, v0
	v_mul_f32_e32 v90, v89, v88
	v_fma_f32 v91, -v83, v90, v89
	v_fmac_f32_e32 v90, v91, v88
	v_fma_f32 v83, -v83, v90, v89
	v_div_fmas_f32 v83, v83, v88, v90
	v_div_fixup_f32 v86, v83, v86, v0
	v_pk_mul_f32 v[84:85], v[84:85], v[86:87]
	s_nop 0
	v_cvt_pk_bf16_f32 v83, v84, v85
	global_store_dwordx2 v[98:99], v[82:83], off offset:96
	v_mov_b32_e32 v82, v222
	v_mov_b32_e32 v83, v223
	v_lshlrev_b32_e32 v0, 16, v82
	v_and_b32_e32 v82, 0xffff0000, v82
	v_mul_f32_e32 v84, 0xbfb8aa3b, v0
	v_mul_f32_e32 v85, 0xbfb8aa3b, v82
	v_exp_f32_e32 v84, v84
	v_exp_f32_e32 v85, v85
	s_nop 0
	v_pk_add_f32 v[84:85], v[84:85], 1.0 op_sel_hi:[1,0]
	s_nop 0
	v_div_scale_f32 v86, s[6:7], v85, v85, v82
	v_rcp_f32_e32 v87, v86
	s_nop 0
	v_fma_f32 v88, -v86, v87, 1.0
	v_fmac_f32_e32 v87, v88, v87
	v_div_scale_f32 v88, vcc, v82, v85, v82
	v_mul_f32_e32 v89, v88, v87
	v_fma_f32 v90, -v86, v89, v88
	v_fmac_f32_e32 v89, v90, v87
	v_fma_f32 v86, -v86, v89, v88
	v_div_fmas_f32 v86, v86, v87, v89
	v_div_fixup_f32 v85, v86, v85, v82
	v_div_scale_f32 v82, s[6:7], v84, v84, v0
; DI unsigned pk2(float lo, float hi) { f32x2_t f = {lo, hi}; bf16x2_t v = __builtin_convertvector(f, bf16x2_t); return __builtin_bit_cast(unsigned, v); }
; DI float silu(float v) { return v / (1.f + __expf(-v)); }
; DI void sb_phase(const Params& P, LAS unsigned char* lds) {
;     ...
;               for (int vt = 0; vt < 8; ++vt) { const u32x2 gv = *(const u32x2*)(gp + 16 * vt);
;                   u32x2 wv; wv.x = pk2(o[vt][0] * silu(bflo(gv.x)), o[vt][1] * silu(bfhi(gv.x))); wv.y = pk2(o[vt][2] * silu(bflo(gv.y)), o[vt][3] * silu(bfhi(gv.y)));
;                   *(u32x2*)(yp + 16 * vt) = wv; } }
	v_rcp_f32_e32 v86, v82
	s_nop 0
	v_fma_f32 v87, -v82, v86, 1.0
	v_fmac_f32_e32 v86, v87, v86
	v_div_scale_f32 v87, vcc, v0, v84, v0
	v_mul_f32_e32 v88, v87, v86
	v_fma_f32 v89, -v82, v88, v87
	v_fmac_f32_e32 v88, v89, v86
	v_fma_f32 v82, -v82, v88, v87
	v_div_fmas_f32 v82, v82, v86, v88
	v_div_fixup_f32 v84, v82, v84, v0
	v_pk_mul_f32 v[78:79], v[78:79], v[84:85]
	v_lshlrev_b32_e32 v0, 16, v83
	v_cvt_pk_bf16_f32 v78, v78, v79
	v_and_b32_e32 v79, 0xffff0000, v83
	v_mul_f32_e32 v82, 0xbfb8aa3b, v0
	v_mul_f32_e32 v83, 0xbfb8aa3b, v79
	v_exp_f32_e32 v82, v82
	v_exp_f32_e32 v83, v83
	s_nop 0
	v_pk_add_f32 v[82:83], v[82:83], 1.0 op_sel_hi:[1,0]
	s_nop 0
	v_div_scale_f32 v84, s[6:7], v83, v83, v79
	v_rcp_f32_e32 v85, v84
	s_nop 0
	v_fma_f32 v86, -v84, v85, 1.0
	v_fmac_f32_e32 v85, v86, v85
	v_div_scale_f32 v86, vcc, v79, v83, v79
	v_mul_f32_e32 v87, v86, v85
	v_fma_f32 v88, -v84, v87, v86
	v_fmac_f32_e32 v87, v88, v85
	v_fma_f32 v84, -v84, v87, v86
	v_div_fmas_f32 v84, v84, v85, v87
	v_div_fixup_f32 v83, v84, v83, v79
	v_div_scale_f32 v79, s[6:7], v82, v82, v0
	v_rcp_f32_e32 v84, v79
	s_nop 0
	v_fma_f32 v85, -v79, v84, 1.0
	v_fmac_f32_e32 v84, v85, v84
	v_div_scale_f32 v85, vcc, v0, v82, v0
	v_mul_f32_e32 v86, v85, v84
	v_fma_f32 v87, -v79, v86, v85
	v_fmac_f32_e32 v86, v87, v84
	v_fma_f32 v79, -v79, v86, v85
	v_div_fmas_f32 v79, v79, v84, v86
	v_div_fixup_f32 v82, v79, v82, v0
	v_pk_mul_f32 v[80:81], v[80:81], v[82:83]
	s_nop 0
	v_cvt_pk_bf16_f32 v79, v80, v81
	global_store_dwordx2 v[98:99], v[78:79], off offset:128
	v_mov_b32_e32 v78, v224
	v_mov_b32_e32 v79, v225
	v_lshlrev_b32_e32 v0, 16, v78
	v_and_b32_e32 v78, 0xffff0000, v78
	v_mul_f32_e32 v80, 0xbfb8aa3b, v0
	v_mul_f32_e32 v81, 0xbfb8aa3b, v78
	v_exp_f32_e32 v80, v80
	v_exp_f32_e32 v81, v81
	s_nop 0
	v_pk_add_f32 v[80:81], v[80:81], 1.0 op_sel_hi:[1,0]
	s_nop 0
	v_div_scale_f32 v82, s[6:7], v81, v81, v78
	v_rcp_f32_e32 v83, v82
	s_nop 0
	v_fma_f32 v84, -v82, v83, 1.0
	v_fmac_f32_e32 v83, v84, v83
	v_div_scale_f32 v84, vcc, v78, v81, v78
	v_mul_f32_e32 v85, v84, v83
	v_fma_f32 v86, -v82, v85, v84
	v_fmac_f32_e32 v85, v86, v83
	v_fma_f32 v82, -v82, v85, v84
	v_div_fmas_f32 v82, v82, v83, v85
	v_div_fixup_f32 v81, v82, v81, v78
	v_div_scale_f32 v78, s[6:7], v80, v80, v0
	v_rcp_f32_e32 v82, v78
	s_nop 0
	v_fma_f32 v83, -v78, v82, 1.0
	v_fmac_f32_e32 v82, v83, v82
	v_div_scale_f32 v83, vcc, v0, v80, v0
	v_mul_f32_e32 v84, v83, v82
	v_fma_f32 v85, -v78, v84, v83
	v_fmac_f32_e32 v84, v85, v82
	v_fma_f32 v78, -v78, v84, v83
	v_div_fmas_f32 v78, v78, v82, v84
	v_div_fixup_f32 v80, v78, v80, v0
	v_pk_mul_f32 v[74:75], v[74:75], v[80:81]
	v_lshlrev_b32_e32 v0, 16, v79
	v_cvt_pk_bf16_f32 v74, v74, v75
	v_and_b32_e32 v75, 0xffff0000, v79
	v_mul_f32_e32 v78, 0xbfb8aa3b, v0
	v_mul_f32_e32 v79, 0xbfb8aa3b, v75
	v_exp_f32_e32 v78, v78
	v_exp_f32_e32 v79, v79
	s_nop 0
	v_pk_add_f32 v[78:79], v[78:79], 1.0 op_sel_hi:[1,0]
	s_nop 0
	v_div_scale_f32 v80, s[6:7], v79, v79, v75
	v_rcp_f32_e32 v81, v80
	s_nop 0
	v_fma_f32 v82, -v80, v81, 1.0
	v_fmac_f32_e32 v81, v82, v81
	v_div_scale_f32 v82, vcc, v75, v79, v75
	v_mul_f32_e32 v83, v82, v81
	v_fma_f32 v84, -v80, v83, v82
	v_fmac_f32_e32 v83, v84, v81
	v_fma_f32 v80, -v80, v83, v82
	v_div_fmas_f32 v80, v80, v81, v83
	v_div_fixup_f32 v79, v80, v79, v75
	v_div_scale_f32 v75, s[6:7], v78, v78, v0
	v_rcp_f32_e32 v80, v75
	s_nop 0
	v_fma_f32 v81, -v75, v80, 1.0
	v_fmac_f32_e32 v80, v81, v80
	v_div_scale_f32 v81, vcc, v0, v78, v0
	v_mul_f32_e32 v82, v81, v80
	v_fma_f32 v83, -v75, v82, v81
	v_fmac_f32_e32 v82, v83, v80
	v_fma_f32 v75, -v75, v82, v81
	v_div_fmas_f32 v75, v75, v80, v82
	v_div_fixup_f32 v78, v75, v78, v0
	v_pk_mul_f32 v[76:77], v[76:77], v[78:79]
	s_nop 0
	v_cvt_pk_bf16_f32 v75, v76, v77
	global_store_dwordx2 v[98:99], v[74:75], off offset:160
	v_mov_b32_e32 v74, v226
	v_mov_b32_e32 v75, v227
	v_lshlrev_b32_e32 v0, 16, v74
	v_and_b32_e32 v74, 0xffff0000, v74
	v_mul_f32_e32 v76, 0xbfb8aa3b, v0
	v_mul_f32_e32 v77, 0xbfb8aa3b, v74
	v_exp_f32_e32 v76, v76
	v_exp_f32_e32 v77, v77
	s_nop 0
	v_pk_add_f32 v[76:77], v[76:77], 1.0 op_sel_hi:[1,0]
	s_nop 0
	v_div_scale_f32 v78, s[6:7], v77, v77, v74
	v_rcp_f32_e32 v79, v78
	s_nop 0
	v_fma_f32 v80, -v78, v79, 1.0
	v_fmac_f32_e32 v79, v80, v79
	v_div_scale_f32 v80, vcc, v74, v77, v74
	v_mul_f32_e32 v81, v80, v79
	v_fma_f32 v82, -v78, v81, v80
	v_fmac_f32_e32 v81, v82, v79
	v_fma_f32 v78, -v78, v81, v80
	v_div_fmas_f32 v78, v78, v79, v81
	v_div_fixup_f32 v77, v78, v77, v74
	v_div_scale_f32 v74, s[6:7], v76, v76, v0
	v_rcp_f32_e32 v78, v74
	s_nop 0
	v_fma_f32 v79, -v74, v78, 1.0
	v_fmac_f32_e32 v78, v79, v78
	v_div_scale_f32 v79, vcc, v0, v76, v0
; DI unsigned pk2(float lo, float hi) { f32x2_t f = {lo, hi}; bf16x2_t v = __builtin_convertvector(f, bf16x2_t); return __builtin_bit_cast(unsigned, v); }
; DI float silu(float v) { return v / (1.f + __expf(-v)); }
; DI void sb_phase(const Params& P, LAS unsigned char* lds) {
;     ...
;               for (int vt = 0; vt < 8; ++vt) { const u32x2 gv = *(const u32x2*)(gp + 16 * vt);
;                   u32x2 wv; wv.x = pk2(o[vt][0] * silu(bflo(gv.x)), o[vt][1] * silu(bfhi(gv.x))); wv.y = pk2(o[vt][2] * silu(bflo(gv.y)), o[vt][3] * silu(bfhi(gv.y)));
;                   *(u32x2*)(yp + 16 * vt) = wv; } }
;             u = nu; r = 0; R = 0.f;
;             if (u >= 2048) break;
; #pragma unroll
;             for (int ks = 0; ks < 4; ++ks) qb[ks] = qn[ks];
; #pragma unroll
;             for (int vt = 0; vt < 8; ++vt) o[vt] = (f32x4){0.f, 0.f, 0.f, 0.f};
	v_mul_f32_e32 v80, v79, v78
	v_fma_f32 v81, -v74, v80, v79
	v_fmac_f32_e32 v80, v81, v78
	v_fma_f32 v74, -v74, v80, v79
	v_div_fmas_f32 v74, v74, v78, v80
	v_div_fixup_f32 v76, v74, v76, v0
	v_pk_mul_f32 v[70:71], v[70:71], v[76:77]
	v_lshlrev_b32_e32 v0, 16, v75
	v_cvt_pk_bf16_f32 v70, v70, v71
	v_and_b32_e32 v71, 0xffff0000, v75
	v_mul_f32_e32 v74, 0xbfb8aa3b, v0
	v_mul_f32_e32 v75, 0xbfb8aa3b, v71
	v_exp_f32_e32 v74, v74
	v_exp_f32_e32 v75, v75
	s_nop 0
	v_pk_add_f32 v[74:75], v[74:75], 1.0 op_sel_hi:[1,0]
	s_nop 0
	v_div_scale_f32 v76, s[6:7], v75, v75, v71
	v_rcp_f32_e32 v77, v76
	s_nop 0
	v_fma_f32 v78, -v76, v77, 1.0
	v_fmac_f32_e32 v77, v78, v77
	v_div_scale_f32 v78, vcc, v71, v75, v71
	v_mul_f32_e32 v79, v78, v77
	v_fma_f32 v80, -v76, v79, v78
	v_fmac_f32_e32 v79, v80, v77
	v_fma_f32 v76, -v76, v79, v78
	v_div_fmas_f32 v76, v76, v77, v79
	v_div_fixup_f32 v75, v76, v75, v71
	v_div_scale_f32 v71, s[6:7], v74, v74, v0
	v_rcp_f32_e32 v76, v71
	s_nop 0
	v_fma_f32 v77, -v71, v76, 1.0
	v_fmac_f32_e32 v76, v77, v76
	v_div_scale_f32 v77, vcc, v0, v74, v0
	v_mul_f32_e32 v78, v77, v76
	v_fma_f32 v79, -v71, v78, v77
	v_fmac_f32_e32 v78, v79, v76
	v_fma_f32 v71, -v71, v78, v77
	v_div_fmas_f32 v71, v71, v76, v78
	v_div_fixup_f32 v74, v71, v74, v0
	v_pk_mul_f32 v[72:73], v[72:73], v[74:75]
	s_nop 0
	v_cvt_pk_bf16_f32 v71, v72, v73
	global_store_dwordx2 v[98:99], v[70:71], off offset:192
	v_mov_b32_e32 v70, v232
	v_mov_b32_e32 v71, v233
	v_lshlrev_b32_e32 v0, 16, v70
	v_and_b32_e32 v70, 0xffff0000, v70
	v_mul_f32_e32 v72, 0xbfb8aa3b, v0
	v_mul_f32_e32 v73, 0xbfb8aa3b, v70
	v_exp_f32_e32 v72, v72
	v_exp_f32_e32 v73, v73
	s_nop 0
	v_pk_add_f32 v[72:73], v[72:73], 1.0 op_sel_hi:[1,0]
	s_nop 0
	v_div_scale_f32 v74, s[6:7], v73, v73, v70
	v_rcp_f32_e32 v75, v74
	s_nop 0
	v_fma_f32 v76, -v74, v75, 1.0
	v_fmac_f32_e32 v75, v76, v75
	v_div_scale_f32 v76, vcc, v70, v73, v70
	v_mul_f32_e32 v77, v76, v75
	v_fma_f32 v78, -v74, v77, v76
	v_fmac_f32_e32 v77, v78, v75
	v_fma_f32 v74, -v74, v77, v76
	v_div_fmas_f32 v74, v74, v75, v77
	v_div_fixup_f32 v73, v74, v73, v70
	v_div_scale_f32 v70, s[6:7], v72, v72, v0
	v_rcp_f32_e32 v74, v70
	s_nop 0
	v_fma_f32 v75, -v70, v74, 1.0
	v_fmac_f32_e32 v74, v75, v74
	v_div_scale_f32 v75, vcc, v0, v72, v0
	v_mul_f32_e32 v76, v75, v74
	v_fma_f32 v77, -v70, v76, v75
	v_fmac_f32_e32 v76, v77, v74
	v_fma_f32 v70, -v70, v76, v75
	v_div_fmas_f32 v70, v70, v74, v76
	v_div_fixup_f32 v72, v70, v72, v0
	v_pk_mul_f32 v[34:35], v[34:35], v[72:73]
	v_lshlrev_b32_e32 v0, 16, v71
	v_cvt_pk_bf16_f32 v34, v34, v35
	v_and_b32_e32 v35, 0xffff0000, v71
	v_mul_f32_e32 v70, 0xbfb8aa3b, v0
	v_mul_f32_e32 v71, 0xbfb8aa3b, v35
	v_exp_f32_e32 v70, v70
	v_exp_f32_e32 v71, v71
	s_nop 0
	v_pk_add_f32 v[70:71], v[70:71], 1.0 op_sel_hi:[1,0]
	s_nop 0
	v_div_scale_f32 v72, s[6:7], v71, v71, v35
	v_rcp_f32_e32 v73, v72
	s_nop 0
	v_fma_f32 v74, -v72, v73, 1.0
	v_fmac_f32_e32 v73, v74, v73
	v_div_scale_f32 v74, vcc, v35, v71, v35
	v_mul_f32_e32 v75, v74, v73
	v_fma_f32 v76, -v72, v75, v74
	v_fmac_f32_e32 v75, v76, v73
	v_fma_f32 v72, -v72, v75, v74
	v_div_fmas_f32 v72, v72, v73, v75
	v_div_fixup_f32 v71, v72, v71, v35
	v_div_scale_f32 v35, s[6:7], v70, v70, v0
	v_rcp_f32_e32 v72, v35
	s_cselect_b64 s[6:7], -1, 0
	v_fma_f32 v73, -v35, v72, 1.0
	v_fmac_f32_e32 v72, v73, v72
	v_div_scale_f32 v73, vcc, v0, v70, v0
	v_mul_f32_e32 v74, v73, v72
	v_fma_f32 v75, -v35, v74, v73
	v_fmac_f32_e32 v74, v75, v72
	v_fma_f32 v35, -v35, v74, v73
	v_div_fmas_f32 v35, v35, v72, v74
	v_div_fixup_f32 v70, v35, v70, v0
	v_pk_mul_f32 v[36:37], v[36:37], v[70:71]
	s_nop 0
	v_cvt_pk_bf16_f32 v35, v36, v37
	global_store_dwordx2 v[98:99], v[34:35], off offset:224
	v_mov_b32_e32 v37, 0
	v_mov_b64_e32 v[100:101], v[4:5]
	v_mov_b32_e32 v36, v37
	v_mov_b32_e32 v35, v37
	v_mov_b32_e32 v34, v37
	v_mov_b32_e32 v73, v37
	v_mov_b32_e32 v72, v37
	v_mov_b32_e32 v71, v37
	v_mov_b32_e32 v70, v37
	v_mov_b32_e32 v77, v37
	v_mov_b32_e32 v76, v37
	v_mov_b32_e32 v75, v37
	v_mov_b32_e32 v74, v37
	v_mov_b32_e32 v81, v37
	v_mov_b32_e32 v80, v37
	v_mov_b32_e32 v79, v37
	v_mov_b32_e32 v78, v37
	v_mov_b32_e32 v85, v37
	v_mov_b32_e32 v84, v37
	v_mov_b32_e32 v83, v37
	v_mov_b32_e32 v82, v37
	v_mov_b32_e32 v89, v37
	v_mov_b32_e32 v88, v37
	v_mov_b32_e32 v87, v37
	v_mov_b32_e32 v86, v37
	v_mov_b32_e32 v93, v37
	v_mov_b32_e32 v92, v37
	v_mov_b32_e32 v91, v37
	v_mov_b32_e32 v90, v37
	v_mov_b32_e32 v97, v37
	v_mov_b32_e32 v96, v37
	v_mov_b32_e32 v95, v37
	v_mov_b32_e32 v94, v37
	v_mov_b32_e32 v183, v37
	v_mov_b64_e32 v[98:99], v[2:3]
	s_mov_b32 s59, s35
	s_and_b64 vcc, exec, s[6:7]
	s_cbranch_vccz .LBB0_49
	s_branch .LBB0_48
